# weight-conversion load loops: issue 8 loads per wait instead of one (all 22 tr_convert instances), plus pipelined rwkv_post loop
# speedup vs baseline: 1.0278x; 1.0190x over previous
.LBB0_13:
	s_or_b64 exec, exec, s[16:17]
	s_add_i32 s15, s15, 16
	s_waitcnt vmcnt(0)
	ds_write_b32 v10, v207 offset:1848
	ds_write_b32 v10, v200
	ds_write_b32 v10, v201 offset:264
	ds_write_b32 v10, v202 offset:528
	ds_write_b32 v10, v203 offset:792
	ds_write_b32 v10, v204 offset:1056
	ds_write_b32 v10, v205 offset:1320
	ds_write_b32 v10, v206 offset:1584
	s_cmp_eq_u32 s15, 64
	v_add_u32_e32 v10, 0x840, v10
	s_cbranch_scc1 .LBB0_5
.LBB0_14:
	v_mov_b32_e32 v200, 0
	v_mov_b32_e32 v201, 0
	v_mov_b32_e32 v202, 0
	v_mov_b32_e32 v203, 0
	v_mov_b32_e32 v204, 0
	v_mov_b32_e32 v205, 0
	v_mov_b32_e32 v206, 0
	v_mov_b32_e32 v207, 0
	s_and_saveexec_b64 s[16:17], vcc
	s_cbranch_execz .LBB0_16
	v_add_u32_e32 v12, s15, v2
	v_mad_i64_i32 v[12:13], s[22:23], v12, s19, v[6:7]
	global_load_dword v200, v[12:13], off nt
.LBB0_16:
	s_or_b64 exec, exec, s[16:17]
	s_and_saveexec_b64 s[16:17], vcc
	s_cbranch_execz .LBB0_18
	v_add3_u32 v11, v2, s15, 2
	v_mad_i64_i32 v[12:13], s[22:23], v11, s19, v[6:7]
	global_load_dword v201, v[12:13], off nt
.LBB0_18:
	s_or_b64 exec, exec, s[16:17]
	s_and_saveexec_b64 s[16:17], vcc
	s_cbranch_execz .LBB0_20
	v_add3_u32 v12, v2, s15, 4
	v_mad_i64_i32 v[12:13], s[22:23], v12, s19, v[6:7]
	global_load_dword v202, v[12:13], off nt
.LBB0_20:
	s_or_b64 exec, exec, s[16:17]
	s_and_saveexec_b64 s[16:17], vcc
	s_cbranch_execz .LBB0_22
	v_add3_u32 v11, v2, s15, 6
	v_mad_i64_i32 v[12:13], s[22:23], v11, s19, v[6:7]
	global_load_dword v203, v[12:13], off nt
.LBB0_22:
	s_or_b64 exec, exec, s[16:17]
	s_and_saveexec_b64 s[16:17], vcc
	s_cbranch_execz .LBB0_24
	v_add3_u32 v12, v2, s15, 8
	v_mad_i64_i32 v[12:13], s[22:23], v12, s19, v[6:7]
	global_load_dword v204, v[12:13], off nt
.LBB0_24:
	s_or_b64 exec, exec, s[16:17]
	s_and_saveexec_b64 s[16:17], vcc
	s_cbranch_execz .LBB0_26
	v_add3_u32 v11, v2, s15, 10
	v_mad_i64_i32 v[12:13], s[22:23], v11, s19, v[6:7]
	global_load_dword v205, v[12:13], off nt
.LBB0_26:
	s_or_b64 exec, exec, s[16:17]
	s_and_saveexec_b64 s[16:17], vcc
	s_cbranch_execz .LBB0_28
	v_add3_u32 v12, v2, s15, 12
	v_mad_i64_i32 v[12:13], s[22:23], v12, s19, v[6:7]
	global_load_dword v206, v[12:13], off nt
.LBB0_28:
	s_or_b64 exec, exec, s[16:17]
	s_and_saveexec_b64 s[16:17], vcc
	s_cbranch_execz .LBB0_13
	v_add3_u32 v11, v2, s15, 14
	v_mad_i64_i32 v[12:13], s[22:23], v11, s19, v[6:7]
	global_load_dword v207, v[12:13], off nt
	s_branch .LBB0_13

.LBB0_35:
	v_mov_b32_e32 v200, 0
	v_mov_b32_e32 v201, 0
	v_mov_b32_e32 v202, 0
	v_mov_b32_e32 v203, 0
	v_mov_b32_e32 v204, 0
	v_mov_b32_e32 v205, 0
	v_mov_b32_e32 v206, 0
	v_mov_b32_e32 v207, 0
	s_and_saveexec_b64 s[16:17], vcc
	s_cbranch_execz .LBB0_37
	v_add_u32_e32 v12, s15, v2
	v_ashrrev_i32_e32 v13, 31, v12
	v_lshlrev_b64 v[12:13], 12, v[12:13]
	v_lshl_add_u64 v[12:13], v[6:7], 0, v[12:13]
	global_load_dword v200, v[12:13], off nt
.LBB0_37:
	s_or_b64 exec, exec, s[16:17]
	s_and_saveexec_b64 s[16:17], vcc
	s_cbranch_execz .LBB0_39
	v_add3_u32 v12, v2, s15, 2
	v_ashrrev_i32_e32 v13, 31, v12
	v_lshlrev_b64 v[12:13], 12, v[12:13]
	v_lshl_add_u64 v[12:13], v[6:7], 0, v[12:13]
	global_load_dword v201, v[12:13], off nt
.LBB0_39:
	s_or_b64 exec, exec, s[16:17]
	s_and_saveexec_b64 s[16:17], vcc
	s_cbranch_execz .LBB0_41
	v_add3_u32 v12, v2, s15, 4
	v_ashrrev_i32_e32 v13, 31, v12
	v_lshlrev_b64 v[12:13], 12, v[12:13]
	v_lshl_add_u64 v[12:13], v[6:7], 0, v[12:13]
	global_load_dword v202, v[12:13], off nt
.LBB0_41:
	s_or_b64 exec, exec, s[16:17]
	s_and_saveexec_b64 s[16:17], vcc
	s_cbranch_execz .LBB0_43
	v_add3_u32 v12, v2, s15, 6
	v_ashrrev_i32_e32 v13, 31, v12
	v_lshlrev_b64 v[12:13], 12, v[12:13]
	v_lshl_add_u64 v[12:13], v[6:7], 0, v[12:13]
	global_load_dword v203, v[12:13], off nt
.LBB0_43:
	s_or_b64 exec, exec, s[16:17]
	s_and_saveexec_b64 s[16:17], vcc
	s_cbranch_execz .LBB0_45
	v_add3_u32 v12, v2, s15, 8
	v_ashrrev_i32_e32 v13, 31, v12
	v_lshlrev_b64 v[12:13], 12, v[12:13]
	v_lshl_add_u64 v[12:13], v[6:7], 0, v[12:13]
	global_load_dword v204, v[12:13], off nt
.LBB0_45:
	s_or_b64 exec, exec, s[16:17]
	s_and_saveexec_b64 s[16:17], vcc
	s_cbranch_execz .LBB0_47
	v_add3_u32 v12, v2, s15, 10
	v_ashrrev_i32_e32 v13, 31, v12
	v_lshlrev_b64 v[12:13], 12, v[12:13]
	v_lshl_add_u64 v[12:13], v[6:7], 0, v[12:13]
	global_load_dword v205, v[12:13], off nt
.LBB0_47:
	s_or_b64 exec, exec, s[16:17]
	s_and_saveexec_b64 s[16:17], vcc
	s_cbranch_execz .LBB0_49
	v_add3_u32 v12, v2, s15, 12
	v_ashrrev_i32_e32 v13, 31, v12
	v_lshlrev_b64 v[12:13], 12, v[12:13]
	v_lshl_add_u64 v[12:13], v[6:7], 0, v[12:13]
	global_load_dword v206, v[12:13], off nt
.LBB0_49:
	s_or_b64 exec, exec, s[16:17]
	s_and_saveexec_b64 s[16:17], vcc
	s_cbranch_execz .LBB0_34
	v_add3_u32 v12, v2, s15, 14
	v_ashrrev_i32_e32 v13, 31, v12
	v_lshlrev_b64 v[12:13], 12, v[12:13]
	v_lshl_add_u64 v[12:13], v[6:7], 0, v[12:13]
	global_load_dword v207, v[12:13], off nt
	s_branch .LBB0_34

.LBB0_55:
	s_or_b64 exec, exec, s[16:17]
	s_add_i32 s15, s15, 16
	s_waitcnt vmcnt(0)
	ds_write_b32 v4, v207 offset:1848
	ds_write_b32 v4, v200
	ds_write_b32 v4, v201 offset:264
	ds_write_b32 v4, v202 offset:528
	ds_write_b32 v4, v203 offset:792
	ds_write_b32 v4, v204 offset:1056
	ds_write_b32 v4, v205 offset:1320
	ds_write_b32 v4, v206 offset:1584
	s_cmp_eq_u32 s15, 64
	v_add_u32_e32 v4, 0x840, v4
	s_cbranch_scc1 .LBB0_53
.LBB0_56:
	v_mov_b32_e32 v200, 0
	v_mov_b32_e32 v201, 0
	v_mov_b32_e32 v202, 0
	v_mov_b32_e32 v203, 0
	v_mov_b32_e32 v204, 0
	v_mov_b32_e32 v205, 0
	v_mov_b32_e32 v206, 0
	v_mov_b32_e32 v207, 0
	s_and_saveexec_b64 s[16:17], vcc
	s_cbranch_execz .LBB0_58
	v_add_u32_e32 v16, s15, v3
	v_ashrrev_i32_e32 v17, 31, v16
	v_lshlrev_b64 v[16:17], 11, v[16:17]
	v_lshl_add_u64 v[16:17], v[8:9], 0, v[16:17]
	global_load_dword v200, v[16:17], off nt
.LBB0_58:
	s_or_b64 exec, exec, s[16:17]
	s_and_saveexec_b64 s[16:17], vcc
	s_cbranch_execz .LBB0_60
	v_add3_u32 v16, v3, s15, 2
	v_ashrrev_i32_e32 v17, 31, v16
	v_lshlrev_b64 v[16:17], 11, v[16:17]
	v_lshl_add_u64 v[16:17], v[8:9], 0, v[16:17]
	global_load_dword v201, v[16:17], off nt
.LBB0_60:
	s_or_b64 exec, exec, s[16:17]
	s_and_saveexec_b64 s[16:17], vcc
	s_cbranch_execz .LBB0_62
	v_add3_u32 v16, v3, s15, 4
	v_ashrrev_i32_e32 v17, 31, v16
	v_lshlrev_b64 v[16:17], 11, v[16:17]
	v_lshl_add_u64 v[16:17], v[8:9], 0, v[16:17]
	global_load_dword v202, v[16:17], off nt
.LBB0_62:
	s_or_b64 exec, exec, s[16:17]
	s_and_saveexec_b64 s[16:17], vcc
	s_cbranch_execz .LBB0_64
	v_add3_u32 v16, v3, s15, 6
	v_ashrrev_i32_e32 v17, 31, v16
	v_lshlrev_b64 v[16:17], 11, v[16:17]
	v_lshl_add_u64 v[16:17], v[8:9], 0, v[16:17]
	global_load_dword v203, v[16:17], off nt
.LBB0_64:
	s_or_b64 exec, exec, s[16:17]
	s_and_saveexec_b64 s[16:17], vcc
	s_cbranch_execz .LBB0_66
	v_add3_u32 v16, v3, s15, 8
	v_ashrrev_i32_e32 v17, 31, v16
	v_lshlrev_b64 v[16:17], 11, v[16:17]
	v_lshl_add_u64 v[16:17], v[8:9], 0, v[16:17]
	global_load_dword v204, v[16:17], off nt
.LBB0_66:
	s_or_b64 exec, exec, s[16:17]
	s_and_saveexec_b64 s[16:17], vcc
	s_cbranch_execz .LBB0_68
	v_add3_u32 v16, v3, s15, 10
	v_ashrrev_i32_e32 v17, 31, v16
	v_lshlrev_b64 v[16:17], 11, v[16:17]
	v_lshl_add_u64 v[16:17], v[8:9], 0, v[16:17]
	global_load_dword v205, v[16:17], off nt
.LBB0_68:
	s_or_b64 exec, exec, s[16:17]
	s_and_saveexec_b64 s[16:17], vcc
	s_cbranch_execz .LBB0_70
	v_add3_u32 v16, v3, s15, 12
	v_ashrrev_i32_e32 v17, 31, v16
	v_lshlrev_b64 v[16:17], 11, v[16:17]
	v_lshl_add_u64 v[16:17], v[8:9], 0, v[16:17]
	global_load_dword v206, v[16:17], off nt
.LBB0_70:
	s_or_b64 exec, exec, s[16:17]
	s_and_saveexec_b64 s[16:17], vcc
	s_cbranch_execz .LBB0_55
	v_add3_u32 v16, v3, s15, 14
	v_ashrrev_i32_e32 v17, 31, v16
	v_lshlrev_b64 v[16:17], 11, v[16:17]
	v_lshl_add_u64 v[16:17], v[8:9], 0, v[16:17]
	global_load_dword v207, v[16:17], off nt
	s_branch .LBB0_55

.LBB0_75:
	s_or_b64 exec, exec, s[16:17]
	s_add_i32 s15, s15, 16
	s_waitcnt vmcnt(0)
	ds_write_b32 v8, v207 offset:1848
	ds_write_b32 v8, v200
	ds_write_b32 v8, v201 offset:264
	ds_write_b32 v8, v202 offset:528
	ds_write_b32 v8, v203 offset:792
	ds_write_b32 v8, v204 offset:1056
	ds_write_b32 v8, v205 offset:1320
	ds_write_b32 v8, v206 offset:1584
	s_cmp_eq_u32 s15, 64
	v_add_u32_e32 v8, 0x840, v8
	s_cbranch_scc1 .LBB0_73
.LBB0_76:
	v_mov_b32_e32 v200, 0
	v_mov_b32_e32 v201, 0
	v_mov_b32_e32 v202, 0
	v_mov_b32_e32 v203, 0
	v_mov_b32_e32 v204, 0
	v_mov_b32_e32 v205, 0
	v_mov_b32_e32 v206, 0
	v_mov_b32_e32 v207, 0
	s_and_saveexec_b64 s[16:17], vcc
	s_cbranch_execz .LBB0_78
	v_add_u32_e32 v16, s15, v2
	v_ashrrev_i32_e32 v17, 31, v16
	v_lshlrev_b64 v[16:17], 11, v[16:17]
	v_lshl_add_u64 v[16:17], v[6:7], 0, v[16:17]
	global_load_dword v200, v[16:17], off nt
.LBB0_78:
	s_or_b64 exec, exec, s[16:17]
	s_and_saveexec_b64 s[16:17], vcc
	s_cbranch_execz .LBB0_80
	v_add3_u32 v16, v2, s15, 2
	v_ashrrev_i32_e32 v17, 31, v16
	v_lshlrev_b64 v[16:17], 11, v[16:17]
	v_lshl_add_u64 v[16:17], v[6:7], 0, v[16:17]
	global_load_dword v201, v[16:17], off nt
.LBB0_80:
	s_or_b64 exec, exec, s[16:17]
	s_and_saveexec_b64 s[16:17], vcc
	s_cbranch_execz .LBB0_82
	v_add3_u32 v16, v2, s15, 4
	v_ashrrev_i32_e32 v17, 31, v16
	v_lshlrev_b64 v[16:17], 11, v[16:17]
	v_lshl_add_u64 v[16:17], v[6:7], 0, v[16:17]
	global_load_dword v202, v[16:17], off nt
.LBB0_82:
	s_or_b64 exec, exec, s[16:17]
	s_and_saveexec_b64 s[16:17], vcc
	s_cbranch_execz .LBB0_84
	v_add3_u32 v16, v2, s15, 6
	v_ashrrev_i32_e32 v17, 31, v16
	v_lshlrev_b64 v[16:17], 11, v[16:17]
	v_lshl_add_u64 v[16:17], v[6:7], 0, v[16:17]
	global_load_dword v203, v[16:17], off nt
.LBB0_84:
	s_or_b64 exec, exec, s[16:17]
	s_and_saveexec_b64 s[16:17], vcc
	s_cbranch_execz .LBB0_86
	v_add3_u32 v16, v2, s15, 8
	v_ashrrev_i32_e32 v17, 31, v16
	v_lshlrev_b64 v[16:17], 11, v[16:17]
	v_lshl_add_u64 v[16:17], v[6:7], 0, v[16:17]
	global_load_dword v204, v[16:17], off nt
.LBB0_86:
	s_or_b64 exec, exec, s[16:17]
	s_and_saveexec_b64 s[16:17], vcc
	s_cbranch_execz .LBB0_88
	v_add3_u32 v16, v2, s15, 10
	v_ashrrev_i32_e32 v17, 31, v16
	v_lshlrev_b64 v[16:17], 11, v[16:17]
	v_lshl_add_u64 v[16:17], v[6:7], 0, v[16:17]
	global_load_dword v205, v[16:17], off nt
.LBB0_88:
	s_or_b64 exec, exec, s[16:17]
	s_and_saveexec_b64 s[16:17], vcc
	s_cbranch_execz .LBB0_90
	v_add3_u32 v16, v2, s15, 12
	v_ashrrev_i32_e32 v17, 31, v16
	v_lshlrev_b64 v[16:17], 11, v[16:17]
	v_lshl_add_u64 v[16:17], v[6:7], 0, v[16:17]
	global_load_dword v206, v[16:17], off nt
.LBB0_90:
	s_or_b64 exec, exec, s[16:17]
	s_and_saveexec_b64 s[16:17], vcc
	s_cbranch_execz .LBB0_75
	v_add3_u32 v16, v2, s15, 14
	v_ashrrev_i32_e32 v17, 31, v16
	v_lshlrev_b64 v[16:17], 11, v[16:17]
	v_lshl_add_u64 v[16:17], v[6:7], 0, v[16:17]
	global_load_dword v207, v[16:17], off nt
	s_branch .LBB0_75

.LBB0_97:
	v_mov_b32_e32 v200, 0
	v_mov_b32_e32 v201, 0
	v_mov_b32_e32 v202, 0
	v_mov_b32_e32 v203, 0
	v_mov_b32_e32 v204, 0
	v_mov_b32_e32 v205, 0
	v_mov_b32_e32 v206, 0
	v_mov_b32_e32 v207, 0
	s_and_saveexec_b64 s[16:17], vcc
	s_cbranch_execz .LBB0_99
	v_add_u32_e32 v12, s15, v2
	v_ashrrev_i32_e32 v13, 31, v12
	v_lshlrev_b64 v[12:13], 11, v[12:13]
	v_lshl_add_u64 v[12:13], v[6:7], 0, v[12:13]
	global_load_dword v200, v[12:13], off nt
.LBB0_99:
	s_or_b64 exec, exec, s[16:17]
	s_and_saveexec_b64 s[16:17], vcc
	s_cbranch_execz .LBB0_101
	v_add3_u32 v12, v2, s15, 2
	v_ashrrev_i32_e32 v13, 31, v12
	v_lshlrev_b64 v[12:13], 11, v[12:13]
	v_lshl_add_u64 v[12:13], v[6:7], 0, v[12:13]
	global_load_dword v201, v[12:13], off nt
.LBB0_101:
	s_or_b64 exec, exec, s[16:17]
	s_and_saveexec_b64 s[16:17], vcc
	s_cbranch_execz .LBB0_103
	v_add3_u32 v12, v2, s15, 4
	v_ashrrev_i32_e32 v13, 31, v12
	v_lshlrev_b64 v[12:13], 11, v[12:13]
	v_lshl_add_u64 v[12:13], v[6:7], 0, v[12:13]
	global_load_dword v202, v[12:13], off nt
.LBB0_103:
	s_or_b64 exec, exec, s[16:17]
	s_and_saveexec_b64 s[16:17], vcc
	s_cbranch_execz .LBB0_105
	v_add3_u32 v12, v2, s15, 6
	v_ashrrev_i32_e32 v13, 31, v12
	v_lshlrev_b64 v[12:13], 11, v[12:13]
	v_lshl_add_u64 v[12:13], v[6:7], 0, v[12:13]
	global_load_dword v203, v[12:13], off nt
.LBB0_105:
	s_or_b64 exec, exec, s[16:17]
	s_and_saveexec_b64 s[16:17], vcc
	s_cbranch_execz .LBB0_107
	v_add3_u32 v12, v2, s15, 8
	v_ashrrev_i32_e32 v13, 31, v12
	v_lshlrev_b64 v[12:13], 11, v[12:13]
	v_lshl_add_u64 v[12:13], v[6:7], 0, v[12:13]
	global_load_dword v204, v[12:13], off nt
.LBB0_107:
	s_or_b64 exec, exec, s[16:17]
	s_and_saveexec_b64 s[16:17], vcc
	s_cbranch_execz .LBB0_109
	v_add3_u32 v12, v2, s15, 10
	v_ashrrev_i32_e32 v13, 31, v12
	v_lshlrev_b64 v[12:13], 11, v[12:13]
	v_lshl_add_u64 v[12:13], v[6:7], 0, v[12:13]
	global_load_dword v205, v[12:13], off nt
.LBB0_109:
	s_or_b64 exec, exec, s[16:17]
	s_and_saveexec_b64 s[16:17], vcc
	s_cbranch_execz .LBB0_111
	v_add3_u32 v12, v2, s15, 12
	v_ashrrev_i32_e32 v13, 31, v12
	v_lshlrev_b64 v[12:13], 11, v[12:13]
	v_lshl_add_u64 v[12:13], v[6:7], 0, v[12:13]
	global_load_dword v206, v[12:13], off nt
.LBB0_111:
	s_or_b64 exec, exec, s[16:17]
	s_and_saveexec_b64 s[16:17], vcc
	s_cbranch_execz .LBB0_96
	v_add3_u32 v12, v2, s15, 14
	v_ashrrev_i32_e32 v13, 31, v12
	v_lshlrev_b64 v[12:13], 11, v[12:13]
	v_lshl_add_u64 v[12:13], v[6:7], 0, v[12:13]
	global_load_dword v207, v[12:13], off nt
	s_branch .LBB0_96

.LBB0_117:
	s_add_u32 s18, s18, 0x58000
	s_addc_u32 s19, s19, 0
	s_waitcnt vmcnt(0)
	ds_write_b32 v2, v207 offset:1848
	ds_write_b32 v2, v200
	ds_write_b32 v2, v201 offset:264
	ds_write_b32 v2, v202 offset:528
	ds_write_b32 v2, v203 offset:792
	ds_write_b32 v2, v204 offset:1056
	ds_write_b32 v2, v205 offset:1320
	ds_write_b32 v2, v206 offset:1584
	s_cmp_eq_u32 s18, 0x160000
	v_add_u32_e32 v2, 0x840, v2
	s_cbranch_scc1 .LBB0_115
.LBB0_118:
	v_mov_b32_e32 v200, 0
	v_mov_b32_e32 v201, 0
	v_mov_b32_e32 v202, 0
	v_mov_b32_e32 v203, 0
	v_mov_b32_e32 v204, 0
	v_mov_b32_e32 v205, 0
	v_mov_b32_e32 v206, 0
	v_mov_b32_e32 v207, 0
	s_and_b64 vcc, exec, s[4:5]
	s_cbranch_vccnz .LBB0_120
	v_lshl_add_u64 v[38:39], v[20:21], 0, s[18:19]
	global_load_dword v200, v[38:39], off nt
.LBB0_120:
	s_and_b64 vcc, exec, s[4:5]
	s_cbranch_vccnz .LBB0_122
	v_lshl_add_u64 v[36:37], v[18:19], 0, s[18:19]
	global_load_dword v201, v[36:37], off nt
.LBB0_122:
	s_and_b64 vcc, exec, s[4:5]
	s_cbranch_vccnz .LBB0_124
	v_lshl_add_u64 v[38:39], v[16:17], 0, s[18:19]
	global_load_dword v202, v[38:39], off nt
.LBB0_124:
	s_and_b64 vcc, exec, s[4:5]
	s_cbranch_vccnz .LBB0_126
	v_lshl_add_u64 v[36:37], v[14:15], 0, s[18:19]
	global_load_dword v203, v[36:37], off nt
.LBB0_126:
	s_and_b64 vcc, exec, s[4:5]
	s_cbranch_vccnz .LBB0_128
	v_lshl_add_u64 v[38:39], v[12:13], 0, s[18:19]
	global_load_dword v204, v[38:39], off nt
.LBB0_128:
	s_and_b64 vcc, exec, s[4:5]
	s_cbranch_vccnz .LBB0_130
	v_lshl_add_u64 v[36:37], v[10:11], 0, s[18:19]
	global_load_dword v205, v[36:37], off nt
.LBB0_130:
	s_and_b64 vcc, exec, s[4:5]
	s_cbranch_vccnz .LBB0_132
	v_lshl_add_u64 v[38:39], v[8:9], 0, s[18:19]
	global_load_dword v206, v[38:39], off nt
.LBB0_132:
	s_and_b64 vcc, exec, s[4:5]
	s_cbranch_vccnz .LBB0_117
	v_lshl_add_u64 v[36:37], v[6:7], 0, s[18:19]
	global_load_dword v207, v[36:37], off nt
	s_branch .LBB0_117

.LBB0_1042:
	s_or_b64 exec, exec, s[4:5]
	s_mov_b32 s0, s69
	s_waitcnt lgkmcnt(0)
	s_barrier
	s_lshl_b32 s0, s0, 6
	v_readlane_b32 s1, v248, 3
	s_add_i32 s0, s0, s1
	v_mbcnt_lo_u32_b32 v1, -1, 0
	v_mbcnt_hi_u32_b32 v1, -1, v1
	s_mov_b64 s[8:9], s[70:71]
	v_add_u32_e32 v0, s0, v1
	v_ashrrev_i32_e32 v34, 4, v0
	s_mov_b32 s0, 0x80000
	v_cmp_gt_i32_e32 vcc, s0, v34
	s_and_saveexec_b64 s[4:5], vcc
	v_readlane_b32 s66, v248, 10
	s_cbranch_execz .LBB0_1047
	s_load_dwordx2 s[6:7], s[8:9], 0xd8
	s_load_dwordx2 s[10:11], s[8:9], 0x40
	s_load_dwordx4 s[12:15], s[8:9], 0x88
	v_lshlrev_b32_e32 v1, 2, v1
	v_and_b32_e32 v1, 60, v1
	v_bfe_u32 v4, v0, 4, 3
	v_lshl_or_b32 v0, v4, 6, v1
	v_mov_b32_e32 v13, 0
	v_lshlrev_b32_e32 v12, 2, v0
	s_waitcnt lgkmcnt(0)
	v_lshl_add_u64 v[14:15], s[12:13], 0, v[12:13]
	v_lshl_add_u64 v[16:17], s[14:15], 0, v[12:13]
	v_lshl_add_u64 v[2:3], s[10:11], 0, v[12:13]
	s_mov_b64 s[8:9], 0x1000
	v_lshlrev_b32_e32 v12, 2, v4
	v_readlane_b32 s0, v248, 0
	v_lshl_add_u64 v[18:19], v[2:3], 0, s[8:9]
	v_lshl_add_u64 v[2:3], s[6:7], 0, v[12:13]
	s_mov_b64 s[8:9], 0x2200000
	v_lshlrev_b32_e32 v12, 1, v0
	v_readlane_b32 s1, v248, 1
	v_lshl_add_u64 v[20:21], v[2:3], 0, s[8:9]
	v_lshl_add_u64 v[2:3], s[6:7], 0, v[12:13]
	s_mov_b64 s[8:9], 0x16c00000
	s_lshl_b32 s0, s0, 5
	v_lshl_add_u64 v[22:23], v[2:3], 0, s[8:9]
	s_mov_b64 s[8:9], 0
	v_lshlrev_b32_e32 v12, 1, v0
	s_mov_b64 s[10:11], 0xac00400
	s_movk_i32 s1, 0x1220
	s_mov_b64 s[12:13], 0x22c01400
	v_mov_b32_e32 v35, 0x3a27c5ac
	s_mov_b32 s3, 0x7ffff
	global_load_dwordx4 v[50:53], v[14:15], off
	global_load_dwordx4 v[54:57], v[16:17], off
	global_load_dwordx4 v[58:61], v[18:19], off
	v_mov_b32_e32 v86, 0xffffe5e0
	v_mov_b32_e32 v87, 0xffff
	v_ashrrev_i32_e32 v76, 3, v34
	v_min_i32_e32 v76, v76, v87
	v_ashrrev_i32_e32 v77, 31, v76
	v_lshlrev_b64 v[78:79], 11, v[76:77]
	v_lshl_add_u64 v[80:81], s[6:7], 0, v[78:79]
	v_lshl_add_u64 v[74:75], v[80:81], 0, v[12:13]
	v_lshl_add_u64 v[74:75], v[74:75], 0, s[10:11]
	v_mad_i64_i32 v[80:81], vcc, v76, s1, v[80:81]
	v_lshl_add_u64 v[80:81], v[80:81], 0, v[12:13]
	v_lshl_add_u64 v[80:81], v[80:81], 0, s[12:13]
	global_load_dwordx2 v[64:65], v[74:75], off
	global_load_dwordx2 v[66:67], v[80:81], off
	v_and_b32_e32 v82, 0xfff8, v34
	v_cmp_ne_u32_e32 vcc, 0, v82
	v_lshlrev_b64 v[78:79], 10, v[76:77]
	v_lshl_add_u64 v[78:79], v[22:23], 0, v[78:79]
	v_cndmask_b32_e64 v73, 0, 1, vcc
	v_cndmask_b32_e32 v82, 0, v86, vcc
	v_ashrrev_i32_e32 v83, 31, v82
	v_lshl_add_u64 v[84:85], v[80:81], 0, v[82:83]
	global_load_dwordx2 v[68:69], v[84:85], off
	global_load_dwordx2 v[70:71], v[78:79], off
	v_lshlrev_b64 v[78:79], 5, v[76:77]
	v_lshl_add_u64 v[78:79], v[20:21], 0, v[78:79]
	global_load_dword v72, v[78:79], off
	s_waitcnt vmcnt(0)
.Lpost_loop_P0:
	v_mov_b64_e32 v[30:31], v[64:65]
	v_mov_b64_e32 v[28:29], v[66:67]
	v_mov_b64_e32 v[62:63], v[68:69]
	v_mov_b64_e32 v[32:33], v[70:71]
	v_mov_b32_e32 v24, v72
	v_mov_b64_e32 v[26:27], v[74:75]
	v_mov_b32_e32 v89, v73
	v_add_u32_e32 v88, s0, v34
	v_ashrrev_i32_e32 v76, 3, v88
	v_min_i32_e32 v76, v76, v87
	v_ashrrev_i32_e32 v77, 31, v76
	v_lshlrev_b64 v[78:79], 11, v[76:77]
	v_lshl_add_u64 v[80:81], s[6:7], 0, v[78:79]
	v_lshl_add_u64 v[74:75], v[80:81], 0, v[12:13]
	v_lshl_add_u64 v[74:75], v[74:75], 0, s[10:11]
	v_mad_i64_i32 v[80:81], vcc, v76, s1, v[80:81]
	v_lshl_add_u64 v[80:81], v[80:81], 0, v[12:13]
	v_lshl_add_u64 v[80:81], v[80:81], 0, s[12:13]
	global_load_dwordx2 v[64:65], v[74:75], off
	global_load_dwordx2 v[66:67], v[80:81], off
	v_and_b32_e32 v82, 0xfff8, v88
	v_cmp_ne_u32_e32 vcc, 0, v82
	v_lshlrev_b64 v[78:79], 10, v[76:77]
	v_lshl_add_u64 v[78:79], v[22:23], 0, v[78:79]
	v_cndmask_b32_e64 v73, 0, 1, vcc
	v_cndmask_b32_e32 v82, 0, v86, vcc
	v_ashrrev_i32_e32 v83, 31, v82
	v_lshl_add_u64 v[84:85], v[80:81], 0, v[82:83]
	global_load_dwordx2 v[68:69], v[84:85], off
	global_load_dwordx2 v[70:71], v[78:79], off
	v_lshlrev_b64 v[78:79], 5, v[76:77]
	v_lshl_add_u64 v[78:79], v[20:21], 0, v[78:79]
	global_load_dword v72, v[78:79], off
	v_lshlrev_b32_e32 v36, 16, v62
	v_and_b32_e32 v38, 0xffff0000, v62
	v_lshlrev_b32_e32 v37, 16, v63
	v_and_b32_e32 v39, 0xffff0000, v63
	v_cmp_ne_u32_e32 vcc, 0, v89
	v_lshlrev_b32_e32 v41, 16, v31
	v_lshlrev_b32_e32 v40, 16, v30
	v_cndmask_b32_e32 v36, 0, v36, vcc
	v_cndmask_b32_e32 v37, 0, v37, vcc
	v_cndmask_b32_e32 v38, 0, v38, vcc
	v_cndmask_b32_e32 v39, 0, v39, vcc
	v_and_b32_e32 v31, 0xffff0000, v31
	v_and_b32_e32 v30, 0xffff0000, v30
	v_lshlrev_b32_e32 v42, 16, v28
	v_and_b32_e32 v43, 0xffff0000, v28
	v_lshlrev_b32_e32 v28, 16, v29
	v_sub_f32_e32 v45, v38, v43
	v_sub_f32_e32 v44, v36, v42
	v_sub_f32_e32 v38, v37, v28
	v_pk_add_f32 v[36:37], v[40:41], v[30:31]
	v_and_b32_e32 v29, 0xffff0000, v29
	v_add_f32_e32 v25, v36, v37
	v_sub_f32_e32 v39, v39, v29
	v_pk_fma_f32 v[10:11], v[60:61], v[38:39], v[28:29]
	v_add_f32_dpp v25, v25, v25 quad_perm:[1,0,3,2] row_mask:0xf bank_mask:0xf bound_ctrl:1
	v_pk_fma_f32 v[8:9], v[58:59], v[44:45], v[42:43]
	s_nop 0
	v_add_f32_dpp v25, v25, v25 quad_perm:[2,3,0,1] row_mask:0xf bank_mask:0xf bound_ctrl:1
	s_nop 1
	v_add_f32_dpp v25, v25, v25 row_half_mirror row_mask:0xf bank_mask:0xf bound_ctrl:1
	s_nop 1
	v_add_f32_dpp v25, v25, v25 row_ror:8 row_mask:0xf bank_mask:0xf bound_ctrl:1
	v_fmac_f32_e32 v30, 0xbc800000, v25
	v_fmac_f32_e32 v31, 0xbc800000, v25
	v_fmac_f32_e32 v41, 0xbc800000, v25
	v_fmac_f32_e32 v40, 0xbc800000, v25
	v_mov_b32_e32 v36, v41
	v_mov_b32_e32 v37, v31
	v_mov_b32_e32 v41, v30
	v_pk_mul_f32 v[30:31], v[36:37], v[36:37]
	v_pk_mul_f32 v[46:47], v[40:41], v[40:41]
	s_nop 0
	v_pk_mov_b32 v[48:49], v[46:47], v[30:31] op_sel:[1,0]
	v_mov_b32_e32 v47, v31
	v_pk_add_f32 v[30:31], v[48:49], v[46:47]
	s_nop 0
	v_add_f32_e32 v25, v30, v31
	s_nop 1
	v_add_f32_dpp v25, v25, v25 quad_perm:[1,0,3,2] row_mask:0xf bank_mask:0xf bound_ctrl:1
	s_nop 1
	v_add_f32_dpp v25, v25, v25 quad_perm:[2,3,0,1] row_mask:0xf bank_mask:0xf bound_ctrl:1
	s_nop 1
	v_add_f32_dpp v25, v25, v25 row_half_mirror row_mask:0xf bank_mask:0xf bound_ctrl:1
	s_nop 1
	v_add_f32_dpp v25, v25, v25 row_ror:8 row_mask:0xf bank_mask:0xf bound_ctrl:1
	v_fmamk_f32 v25, v25, 0x3c800000, v35
	v_rsq_f32_e32 v30, v25
	s_nop 0
	v_pk_mul_f32 v[28:29], v[40:41], v[30:31] op_sel_hi:[1,0]
	v_pk_mul_f32 v[30:31], v[36:37], v[30:31] op_sel_hi:[1,0]
	v_pk_fma_f32 v[0:1], v[50:51], v[28:29], v[54:55]
	v_pk_fma_f32 v[2:3], v[52:53], v[30:31], v[56:57]
	v_lshlrev_b32_e32 v4, 16, v32
	v_and_b32_e32 v5, 0xffff0000, v32
	v_lshlrev_b32_e32 v6, 16, v33
	v_and_b32_e32 v7, 0xffff0000, v33
	v_pk_fma_f32 v[0:1], v[8:9], v[24:25], v[0:1] op_sel_hi:[1,0,1]
	v_pk_fma_f32 v[2:3], v[10:11], v[24:25], v[2:3] op_sel_hi:[1,0,1]
	v_pk_mul_f32 v[0:1], v[0:1], v[4:5]
	v_pk_mul_f32 v[2:3], v[2:3], v[6:7]
	v_cvt_pk_bf16_f32 v0, v0, v1
	v_cvt_pk_bf16_f32 v1, v2, v3
	global_store_dwordx2 v[26:27], v[0:1], off
	v_mov_b32_e32 v34, v88
	v_cmp_lt_i32_e32 vcc, s3, v34
	s_or_b64 s[8:9], vcc, s[8:9]
	s_waitcnt vmcnt(1)
	s_andn2_b64 exec, exec, s[8:9]
	s_cbranch_execnz .Lpost_loop_P0
	s_branch .LBB0_1047

.LBB0_1441:
	s_or_b64 exec, exec, s[18:19]
	s_add_i32 s7, s7, 16
	s_waitcnt vmcnt(0)
	ds_write_b32 v8, v207 offset:1848
	ds_write_b32 v8, v200
	ds_write_b32 v8, v201 offset:264
	ds_write_b32 v8, v202 offset:528
	ds_write_b32 v8, v203 offset:792
	ds_write_b32 v8, v204 offset:1056
	ds_write_b32 v8, v205 offset:1320
	ds_write_b32 v8, v206 offset:1584
	s_cmp_eq_u32 s7, 64
	v_add_u32_e32 v8, 0x840, v8
	s_cbranch_scc1 .LBB0_1437
.LBB0_1442:
	v_mov_b32_e32 v200, 0
	v_mov_b32_e32 v201, 0
	v_mov_b32_e32 v202, 0
	v_mov_b32_e32 v203, 0
	v_mov_b32_e32 v204, 0
	v_mov_b32_e32 v205, 0
	v_mov_b32_e32 v206, 0
	v_mov_b32_e32 v207, 0
	s_and_saveexec_b64 s[18:19], vcc
	s_cbranch_execz .LBB0_1444
	v_add_u32_e32 v10, s7, v0
	v_mad_i64_i32 v[10:11], s[20:21], v10, s4, v[4:5]
	global_load_dword v200, v[10:11], off nt
.LBB0_1444:
	s_or_b64 exec, exec, s[18:19]
	s_and_saveexec_b64 s[18:19], vcc
	s_cbranch_execz .LBB0_1446
	v_add3_u32 v9, v0, s7, 2
	v_mad_i64_i32 v[10:11], s[20:21], v9, s4, v[4:5]
	global_load_dword v201, v[10:11], off nt
.LBB0_1446:
	s_or_b64 exec, exec, s[18:19]
	s_and_saveexec_b64 s[18:19], vcc
	s_cbranch_execz .LBB0_1448
	v_add3_u32 v10, v0, s7, 4
	v_mad_i64_i32 v[10:11], s[20:21], v10, s4, v[4:5]
	global_load_dword v202, v[10:11], off nt
.LBB0_1448:
	s_or_b64 exec, exec, s[18:19]
	s_and_saveexec_b64 s[18:19], vcc
	s_cbranch_execz .LBB0_1450
	v_add3_u32 v9, v0, s7, 6
	v_mad_i64_i32 v[10:11], s[20:21], v9, s4, v[4:5]
	global_load_dword v203, v[10:11], off nt
.LBB0_1450:
	s_or_b64 exec, exec, s[18:19]
	s_and_saveexec_b64 s[18:19], vcc
	s_cbranch_execz .LBB0_1452
	v_add3_u32 v10, v0, s7, 8
	v_mad_i64_i32 v[10:11], s[20:21], v10, s4, v[4:5]
	global_load_dword v204, v[10:11], off nt
.LBB0_1452:
	s_or_b64 exec, exec, s[18:19]
	s_and_saveexec_b64 s[18:19], vcc
	s_cbranch_execz .LBB0_1454
	v_add3_u32 v9, v0, s7, 10
	v_mad_i64_i32 v[10:11], s[20:21], v9, s4, v[4:5]
	global_load_dword v205, v[10:11], off nt
.LBB0_1454:
	s_or_b64 exec, exec, s[18:19]
	s_and_saveexec_b64 s[18:19], vcc
	s_cbranch_execz .LBB0_1456
	v_add3_u32 v10, v0, s7, 12
	v_mad_i64_i32 v[10:11], s[20:21], v10, s4, v[4:5]
	global_load_dword v206, v[10:11], off nt
.LBB0_1456:
	s_or_b64 exec, exec, s[18:19]
	s_and_saveexec_b64 s[18:19], vcc
	s_cbranch_execz .LBB0_1441
	v_add3_u32 v9, v0, s7, 14
	v_mad_i64_i32 v[10:11], s[20:21], v9, s4, v[4:5]
	global_load_dword v207, v[10:11], off nt
	s_branch .LBB0_1441

.LBB0_1462:
	s_or_b64 exec, exec, s[18:19]
	s_add_i32 s6, s6, 16
	s_waitcnt vmcnt(0)
	ds_write_b32 v8, v207 offset:1848
	ds_write_b32 v8, v200
	ds_write_b32 v8, v201 offset:264
	ds_write_b32 v8, v202 offset:528
	ds_write_b32 v8, v203 offset:792
	ds_write_b32 v8, v204 offset:1056
	ds_write_b32 v8, v205 offset:1320
	ds_write_b32 v8, v206 offset:1584
	s_cmp_eq_u32 s6, 64
	v_add_u32_e32 v8, 0x840, v8
	s_cbranch_scc1 .LBB0_1460
.LBB0_1463:
	v_mov_b32_e32 v200, 0
	v_mov_b32_e32 v201, 0
	v_mov_b32_e32 v202, 0
	v_mov_b32_e32 v203, 0
	v_mov_b32_e32 v204, 0
	v_mov_b32_e32 v205, 0
	v_mov_b32_e32 v206, 0
	v_mov_b32_e32 v207, 0
	s_and_saveexec_b64 s[18:19], vcc
	s_cbranch_execz .LBB0_1465
	v_add_u32_e32 v10, s6, v0
	v_ashrrev_i32_e32 v11, 31, v10
	v_lshlrev_b64 v[10:11], 12, v[10:11]
	v_lshl_add_u64 v[10:11], v[4:5], 0, v[10:11]
	global_load_dword v200, v[10:11], off nt
.LBB0_1465:
	s_or_b64 exec, exec, s[18:19]
	s_and_saveexec_b64 s[18:19], vcc
	s_cbranch_execz .LBB0_1467
	v_add3_u32 v10, v0, s6, 2
	v_ashrrev_i32_e32 v11, 31, v10
	v_lshlrev_b64 v[10:11], 12, v[10:11]
	v_lshl_add_u64 v[10:11], v[4:5], 0, v[10:11]
	global_load_dword v201, v[10:11], off nt
.LBB0_1467:
	s_or_b64 exec, exec, s[18:19]
	s_and_saveexec_b64 s[18:19], vcc
	s_cbranch_execz .LBB0_1469
	v_add3_u32 v10, v0, s6, 4
	v_ashrrev_i32_e32 v11, 31, v10
	v_lshlrev_b64 v[10:11], 12, v[10:11]
	v_lshl_add_u64 v[10:11], v[4:5], 0, v[10:11]
	global_load_dword v202, v[10:11], off nt
.LBB0_1469:
	s_or_b64 exec, exec, s[18:19]
	s_and_saveexec_b64 s[18:19], vcc
	s_cbranch_execz .LBB0_1471
	v_add3_u32 v10, v0, s6, 6
	v_ashrrev_i32_e32 v11, 31, v10
	v_lshlrev_b64 v[10:11], 12, v[10:11]
	v_lshl_add_u64 v[10:11], v[4:5], 0, v[10:11]
	global_load_dword v203, v[10:11], off nt
.LBB0_1471:
	s_or_b64 exec, exec, s[18:19]
	s_and_saveexec_b64 s[18:19], vcc
	s_cbranch_execz .LBB0_1473
	v_add3_u32 v10, v0, s6, 8
	v_ashrrev_i32_e32 v11, 31, v10
	v_lshlrev_b64 v[10:11], 12, v[10:11]
	v_lshl_add_u64 v[10:11], v[4:5], 0, v[10:11]
	global_load_dword v204, v[10:11], off nt
.LBB0_1473:
	s_or_b64 exec, exec, s[18:19]
	s_and_saveexec_b64 s[18:19], vcc
	s_cbranch_execz .LBB0_1475
	v_add3_u32 v10, v0, s6, 10
	v_ashrrev_i32_e32 v11, 31, v10
	v_lshlrev_b64 v[10:11], 12, v[10:11]
	v_lshl_add_u64 v[10:11], v[4:5], 0, v[10:11]
	global_load_dword v205, v[10:11], off nt
.LBB0_1475:
	s_or_b64 exec, exec, s[18:19]
	s_and_saveexec_b64 s[18:19], vcc
	s_cbranch_execz .LBB0_1477
	v_add3_u32 v10, v0, s6, 12
	v_ashrrev_i32_e32 v11, 31, v10
	v_lshlrev_b64 v[10:11], 12, v[10:11]
	v_lshl_add_u64 v[10:11], v[4:5], 0, v[10:11]
	global_load_dword v206, v[10:11], off nt
.LBB0_1477:
	s_or_b64 exec, exec, s[18:19]
	s_and_saveexec_b64 s[18:19], vcc
	s_cbranch_execz .LBB0_1462
	v_add3_u32 v10, v0, s6, 14
	v_ashrrev_i32_e32 v11, 31, v10
	v_lshlrev_b64 v[10:11], 12, v[10:11]
	v_lshl_add_u64 v[10:11], v[4:5], 0, v[10:11]
	global_load_dword v207, v[10:11], off nt
	s_branch .LBB0_1462

.LBB0_1483:
	s_add_u32 s20, s20, 0x58000
	s_addc_u32 s21, s21, 0
	s_waitcnt vmcnt(0)
	ds_write_b32 v0, v207 offset:1848
	ds_write_b32 v0, v200
	ds_write_b32 v0, v201 offset:264
	ds_write_b32 v0, v202 offset:528
	ds_write_b32 v0, v203 offset:792
	ds_write_b32 v0, v204 offset:1056
	ds_write_b32 v0, v205 offset:1320
	ds_write_b32 v0, v206 offset:1584
	s_cmp_eq_u32 s20, 0x160000
	v_add_u32_e32 v0, 0x840, v0
	s_cbranch_scc1 .LBB0_1481
.LBB0_1484:
	v_mov_b32_e32 v200, 0
	v_mov_b32_e32 v201, 0
	v_mov_b32_e32 v202, 0
	v_mov_b32_e32 v203, 0
	v_mov_b32_e32 v204, 0
	v_mov_b32_e32 v205, 0
	v_mov_b32_e32 v206, 0
	v_mov_b32_e32 v207, 0
	s_and_b64 vcc, exec, s[8:9]
	s_cbranch_vccnz .LBB0_1486
	v_lshl_add_u64 v[34:35], v[18:19], 0, s[20:21]
	global_load_dword v200, v[34:35], off nt
.LBB0_1486:
	s_and_b64 vcc, exec, s[8:9]
	s_cbranch_vccnz .LBB0_1488
	v_lshl_add_u64 v[34:35], v[16:17], 0, s[20:21]
	global_load_dword v201, v[34:35], off nt
.LBB0_1488:
	s_and_b64 vcc, exec, s[8:9]
	s_cbranch_vccnz .LBB0_1490
	v_lshl_add_u64 v[34:35], v[14:15], 0, s[20:21]
	global_load_dword v202, v[34:35], off nt
.LBB0_1490:
	s_and_b64 vcc, exec, s[8:9]
	s_cbranch_vccnz .LBB0_1492
	v_lshl_add_u64 v[34:35], v[12:13], 0, s[20:21]
	global_load_dword v203, v[34:35], off nt
.LBB0_1492:
	s_and_b64 vcc, exec, s[8:9]
	s_cbranch_vccnz .LBB0_1494
	v_lshl_add_u64 v[34:35], v[10:11], 0, s[20:21]
	global_load_dword v204, v[34:35], off nt
.LBB0_1494:
	s_and_b64 vcc, exec, s[8:9]
	s_cbranch_vccnz .LBB0_1496
	v_lshl_add_u64 v[34:35], v[8:9], 0, s[20:21]
	global_load_dword v205, v[34:35], off nt
.LBB0_1496:
	s_and_b64 vcc, exec, s[8:9]
	s_cbranch_vccnz .LBB0_1498
	v_lshl_add_u64 v[34:35], v[6:7], 0, s[20:21]
	global_load_dword v206, v[34:35], off nt
.LBB0_1498:
	s_and_b64 vcc, exec, s[8:9]
	s_cbranch_vccnz .LBB0_1483
	v_lshl_add_u64 v[34:35], v[4:5], 0, s[20:21]
	global_load_dword v207, v[34:35], off nt
	s_branch .LBB0_1483

.LBB0_1504:
	s_or_b64 exec, exec, s[14:15]
	s_add_i32 s4, s4, 16
	s_waitcnt vmcnt(0)
	ds_write_b32 v8, v207 offset:1848
	ds_write_b32 v8, v200
	ds_write_b32 v8, v201 offset:264
	ds_write_b32 v8, v202 offset:528
	ds_write_b32 v8, v203 offset:792
	ds_write_b32 v8, v204 offset:1056
	ds_write_b32 v8, v205 offset:1320
	ds_write_b32 v8, v206 offset:1584
	s_cmp_eq_u32 s4, 64
	v_add_u32_e32 v8, 0x840, v8
	s_cbranch_scc1 .LBB0_1502
.LBB0_1505:
	v_mov_b32_e32 v200, 0
	v_mov_b32_e32 v201, 0
	v_mov_b32_e32 v202, 0
	v_mov_b32_e32 v203, 0
	v_mov_b32_e32 v204, 0
	v_mov_b32_e32 v205, 0
	v_mov_b32_e32 v206, 0
	v_mov_b32_e32 v207, 0
	s_and_saveexec_b64 s[14:15], vcc
	s_cbranch_execz .LBB0_1507
	v_add_u32_e32 v10, s4, v0
	v_ashrrev_i32_e32 v11, 31, v10
	v_lshlrev_b64 v[10:11], 12, v[10:11]
	v_lshl_add_u64 v[10:11], v[4:5], 0, v[10:11]
	global_load_dword v200, v[10:11], off nt
.LBB0_1507:
	s_or_b64 exec, exec, s[14:15]
	s_and_saveexec_b64 s[14:15], vcc
	s_cbranch_execz .LBB0_1509
	v_add3_u32 v10, v0, s4, 2
	v_ashrrev_i32_e32 v11, 31, v10
	v_lshlrev_b64 v[10:11], 12, v[10:11]
	v_lshl_add_u64 v[10:11], v[4:5], 0, v[10:11]
	global_load_dword v201, v[10:11], off nt
.LBB0_1509:
	s_or_b64 exec, exec, s[14:15]
	s_and_saveexec_b64 s[14:15], vcc
	s_cbranch_execz .LBB0_1511
	v_add3_u32 v10, v0, s4, 4
	v_ashrrev_i32_e32 v11, 31, v10
	v_lshlrev_b64 v[10:11], 12, v[10:11]
	v_lshl_add_u64 v[10:11], v[4:5], 0, v[10:11]
	global_load_dword v202, v[10:11], off nt
.LBB0_1511:
	s_or_b64 exec, exec, s[14:15]
	s_and_saveexec_b64 s[14:15], vcc
	s_cbranch_execz .LBB0_1513
	v_add3_u32 v10, v0, s4, 6
	v_ashrrev_i32_e32 v11, 31, v10
	v_lshlrev_b64 v[10:11], 12, v[10:11]
	v_lshl_add_u64 v[10:11], v[4:5], 0, v[10:11]
	global_load_dword v203, v[10:11], off nt
.LBB0_1513:
	s_or_b64 exec, exec, s[14:15]
	s_and_saveexec_b64 s[14:15], vcc
	s_cbranch_execz .LBB0_1515
	v_add3_u32 v10, v0, s4, 8
	v_ashrrev_i32_e32 v11, 31, v10
	v_lshlrev_b64 v[10:11], 12, v[10:11]
	v_lshl_add_u64 v[10:11], v[4:5], 0, v[10:11]
	global_load_dword v204, v[10:11], off nt
.LBB0_1515:
	s_or_b64 exec, exec, s[14:15]
	s_and_saveexec_b64 s[14:15], vcc
	s_cbranch_execz .LBB0_1517
	v_add3_u32 v10, v0, s4, 10
	v_ashrrev_i32_e32 v11, 31, v10
	v_lshlrev_b64 v[10:11], 12, v[10:11]
	v_lshl_add_u64 v[10:11], v[4:5], 0, v[10:11]
	global_load_dword v205, v[10:11], off nt
.LBB0_1517:
	s_or_b64 exec, exec, s[14:15]
	s_and_saveexec_b64 s[14:15], vcc
	s_cbranch_execz .LBB0_1519
	v_add3_u32 v10, v0, s4, 12
	v_ashrrev_i32_e32 v11, 31, v10
	v_lshlrev_b64 v[10:11], 12, v[10:11]
	v_lshl_add_u64 v[10:11], v[4:5], 0, v[10:11]
	global_load_dword v206, v[10:11], off nt
.LBB0_1519:
	s_or_b64 exec, exec, s[14:15]
	s_and_saveexec_b64 s[14:15], vcc
	s_cbranch_execz .LBB0_1504
	v_add3_u32 v10, v0, s4, 14
	v_ashrrev_i32_e32 v11, 31, v10
	v_lshlrev_b64 v[10:11], 12, v[10:11]
	v_lshl_add_u64 v[10:11], v[4:5], 0, v[10:11]
	global_load_dword v207, v[10:11], off nt
	s_branch .LBB0_1504

.LBB0_2134:
	s_or_b64 exec, exec, s[20:21]
	s_add_i32 s8, s8, 16
	s_waitcnt vmcnt(0)
	ds_write_b32 v8, v207 offset:1848
	ds_write_b32 v8, v200
	ds_write_b32 v8, v201 offset:264
	ds_write_b32 v8, v202 offset:528
	ds_write_b32 v8, v203 offset:792
	ds_write_b32 v8, v204 offset:1056
	ds_write_b32 v8, v205 offset:1320
	ds_write_b32 v8, v206 offset:1584
	s_cmp_eq_u32 s8, 64
	v_add_u32_e32 v8, 0x840, v8
	s_cbranch_scc1 .LBB0_2126
.LBB0_2135:
	v_mov_b32_e32 v200, 0
	v_mov_b32_e32 v201, 0
	v_mov_b32_e32 v202, 0
	v_mov_b32_e32 v203, 0
	v_mov_b32_e32 v204, 0
	v_mov_b32_e32 v205, 0
	v_mov_b32_e32 v206, 0
	v_mov_b32_e32 v207, 0
	s_and_saveexec_b64 s[20:21], vcc
	s_cbranch_execz .LBB0_2137
	v_add_u32_e32 v10, s8, v0
	v_mad_i64_i32 v[10:11], s[22:23], v10, s5, v[4:5]
	global_load_dword v200, v[10:11], off nt
.LBB0_2137:
	s_or_b64 exec, exec, s[20:21]
	s_and_saveexec_b64 s[20:21], vcc
	s_cbranch_execz .LBB0_2139
	v_add3_u32 v9, v0, s8, 2
	v_mad_i64_i32 v[10:11], s[22:23], v9, s5, v[4:5]
	global_load_dword v201, v[10:11], off nt
.LBB0_2139:
	s_or_b64 exec, exec, s[20:21]
	s_and_saveexec_b64 s[20:21], vcc
	s_cbranch_execz .LBB0_2141
	v_add3_u32 v10, v0, s8, 4
	v_mad_i64_i32 v[10:11], s[22:23], v10, s5, v[4:5]
	global_load_dword v202, v[10:11], off nt
.LBB0_2141:
	s_or_b64 exec, exec, s[20:21]
	s_and_saveexec_b64 s[20:21], vcc
	s_cbranch_execz .LBB0_2143
	v_add3_u32 v9, v0, s8, 6
	v_mad_i64_i32 v[10:11], s[22:23], v9, s5, v[4:5]
	global_load_dword v203, v[10:11], off nt
.LBB0_2143:
	s_or_b64 exec, exec, s[20:21]
	s_and_saveexec_b64 s[20:21], vcc
	s_cbranch_execz .LBB0_2145
	v_add3_u32 v10, v0, s8, 8
	v_mad_i64_i32 v[10:11], s[22:23], v10, s5, v[4:5]
	global_load_dword v204, v[10:11], off nt
.LBB0_2145:
	s_or_b64 exec, exec, s[20:21]
	s_and_saveexec_b64 s[20:21], vcc
	s_cbranch_execz .LBB0_2147
	v_add3_u32 v9, v0, s8, 10
	v_mad_i64_i32 v[10:11], s[22:23], v9, s5, v[4:5]
	global_load_dword v205, v[10:11], off nt
.LBB0_2147:
	s_or_b64 exec, exec, s[20:21]
	s_and_saveexec_b64 s[20:21], vcc
	s_cbranch_execz .LBB0_2149
	v_add3_u32 v10, v0, s8, 12
	v_mad_i64_i32 v[10:11], s[22:23], v10, s5, v[4:5]
	global_load_dword v206, v[10:11], off nt
.LBB0_2149:
	s_or_b64 exec, exec, s[20:21]
	s_and_saveexec_b64 s[20:21], vcc
	s_cbranch_execz .LBB0_2134
	v_add3_u32 v9, v0, s8, 14
	v_mad_i64_i32 v[10:11], s[22:23], v9, s5, v[4:5]
	global_load_dword v207, v[10:11], off nt
	s_branch .LBB0_2134

.LBB0_2155:
	s_or_b64 exec, exec, s[20:21]
	s_add_i32 s6, s6, 16
	s_waitcnt vmcnt(0)
	ds_write_b32 v8, v207 offset:1848
	ds_write_b32 v8, v200
	ds_write_b32 v8, v201 offset:264
	ds_write_b32 v8, v202 offset:528
	ds_write_b32 v8, v203 offset:792
	ds_write_b32 v8, v204 offset:1056
	ds_write_b32 v8, v205 offset:1320
	ds_write_b32 v8, v206 offset:1584
	s_cmp_eq_u32 s6, 64
	v_add_u32_e32 v8, 0x840, v8
	s_cbranch_scc1 .LBB0_2153
.LBB0_2156:
	v_mov_b32_e32 v200, 0
	v_mov_b32_e32 v201, 0
	v_mov_b32_e32 v202, 0
	v_mov_b32_e32 v203, 0
	v_mov_b32_e32 v204, 0
	v_mov_b32_e32 v205, 0
	v_mov_b32_e32 v206, 0
	v_mov_b32_e32 v207, 0
	s_and_saveexec_b64 s[20:21], vcc
	s_cbranch_execz .LBB0_2158
	v_add_u32_e32 v10, s6, v0
	v_ashrrev_i32_e32 v11, 31, v10
	v_lshlrev_b64 v[10:11], 12, v[10:11]
	v_lshl_add_u64 v[10:11], v[4:5], 0, v[10:11]
	global_load_dword v200, v[10:11], off nt
.LBB0_2158:
	s_or_b64 exec, exec, s[20:21]
	s_and_saveexec_b64 s[20:21], vcc
	s_cbranch_execz .LBB0_2160
	v_add3_u32 v10, v0, s6, 2
	v_ashrrev_i32_e32 v11, 31, v10
	v_lshlrev_b64 v[10:11], 12, v[10:11]
	v_lshl_add_u64 v[10:11], v[4:5], 0, v[10:11]
	global_load_dword v201, v[10:11], off nt
.LBB0_2160:
	s_or_b64 exec, exec, s[20:21]
	s_and_saveexec_b64 s[20:21], vcc
	s_cbranch_execz .LBB0_2162
	v_add3_u32 v10, v0, s6, 4
	v_ashrrev_i32_e32 v11, 31, v10
	v_lshlrev_b64 v[10:11], 12, v[10:11]
	v_lshl_add_u64 v[10:11], v[4:5], 0, v[10:11]
	global_load_dword v202, v[10:11], off nt
.LBB0_2162:
	s_or_b64 exec, exec, s[20:21]
	s_and_saveexec_b64 s[20:21], vcc
	s_cbranch_execz .LBB0_2164
	v_add3_u32 v10, v0, s6, 6
	v_ashrrev_i32_e32 v11, 31, v10
	v_lshlrev_b64 v[10:11], 12, v[10:11]
	v_lshl_add_u64 v[10:11], v[4:5], 0, v[10:11]
	global_load_dword v203, v[10:11], off nt
.LBB0_2164:
	s_or_b64 exec, exec, s[20:21]
	s_and_saveexec_b64 s[20:21], vcc
	s_cbranch_execz .LBB0_2166
	v_add3_u32 v10, v0, s6, 8
	v_ashrrev_i32_e32 v11, 31, v10
	v_lshlrev_b64 v[10:11], 12, v[10:11]
	v_lshl_add_u64 v[10:11], v[4:5], 0, v[10:11]
	global_load_dword v204, v[10:11], off nt
.LBB0_2166:
	s_or_b64 exec, exec, s[20:21]
	s_and_saveexec_b64 s[20:21], vcc
	s_cbranch_execz .LBB0_2168
	v_add3_u32 v10, v0, s6, 10
	v_ashrrev_i32_e32 v11, 31, v10
	v_lshlrev_b64 v[10:11], 12, v[10:11]
	v_lshl_add_u64 v[10:11], v[4:5], 0, v[10:11]
	global_load_dword v205, v[10:11], off nt
.LBB0_2168:
	s_or_b64 exec, exec, s[20:21]
	s_and_saveexec_b64 s[20:21], vcc
	s_cbranch_execz .LBB0_2170
	v_add3_u32 v10, v0, s6, 12
	v_ashrrev_i32_e32 v11, 31, v10
	v_lshlrev_b64 v[10:11], 12, v[10:11]
	v_lshl_add_u64 v[10:11], v[4:5], 0, v[10:11]
	global_load_dword v206, v[10:11], off nt
.LBB0_2170:
	s_or_b64 exec, exec, s[20:21]
	s_and_saveexec_b64 s[20:21], vcc
	s_cbranch_execz .LBB0_2155
	v_add3_u32 v10, v0, s6, 14
	v_ashrrev_i32_e32 v11, 31, v10
	v_lshlrev_b64 v[10:11], 12, v[10:11]
	v_lshl_add_u64 v[10:11], v[4:5], 0, v[10:11]
	global_load_dword v207, v[10:11], off nt
	s_branch .LBB0_2155

.LBB0_2176:
	s_or_b64 exec, exec, s[20:21]
	s_add_i32 s6, s6, 16
	s_waitcnt vmcnt(0)
	ds_write_b32 v2, v207 offset:1848
	ds_write_b32 v2, v200
	ds_write_b32 v2, v201 offset:264
	ds_write_b32 v2, v202 offset:528
	ds_write_b32 v2, v203 offset:792
	ds_write_b32 v2, v204 offset:1056
	ds_write_b32 v2, v205 offset:1320
	ds_write_b32 v2, v206 offset:1584
	s_cmp_eq_u32 s6, 64
	v_add_u32_e32 v2, 0x840, v2
	s_cbranch_scc1 .LBB0_2174
.LBB0_2177:
	v_mov_b32_e32 v200, 0
	v_mov_b32_e32 v201, 0
	v_mov_b32_e32 v202, 0
	v_mov_b32_e32 v203, 0
	v_mov_b32_e32 v204, 0
	v_mov_b32_e32 v205, 0
	v_mov_b32_e32 v206, 0
	v_mov_b32_e32 v207, 0
	s_and_saveexec_b64 s[20:21], vcc
	s_cbranch_execz .LBB0_2179
	v_add_u32_e32 v14, s6, v1
	v_ashrrev_i32_e32 v15, 31, v14
	v_lshlrev_b64 v[14:15], 11, v[14:15]
	v_lshl_add_u64 v[14:15], v[6:7], 0, v[14:15]
	global_load_dword v200, v[14:15], off nt
.LBB0_2179:
	s_or_b64 exec, exec, s[20:21]
	s_and_saveexec_b64 s[20:21], vcc
	s_cbranch_execz .LBB0_2181
	v_add3_u32 v14, v1, s6, 2
	v_ashrrev_i32_e32 v15, 31, v14
	v_lshlrev_b64 v[14:15], 11, v[14:15]
	v_lshl_add_u64 v[14:15], v[6:7], 0, v[14:15]
	global_load_dword v201, v[14:15], off nt
.LBB0_2181:
	s_or_b64 exec, exec, s[20:21]
	s_and_saveexec_b64 s[20:21], vcc
	s_cbranch_execz .LBB0_2183
	v_add3_u32 v14, v1, s6, 4
	v_ashrrev_i32_e32 v15, 31, v14
	v_lshlrev_b64 v[14:15], 11, v[14:15]
	v_lshl_add_u64 v[14:15], v[6:7], 0, v[14:15]
	global_load_dword v202, v[14:15], off nt
.LBB0_2183:
	s_or_b64 exec, exec, s[20:21]
	s_and_saveexec_b64 s[20:21], vcc
	s_cbranch_execz .LBB0_2185
	v_add3_u32 v14, v1, s6, 6
	v_ashrrev_i32_e32 v15, 31, v14
	v_lshlrev_b64 v[14:15], 11, v[14:15]
	v_lshl_add_u64 v[14:15], v[6:7], 0, v[14:15]
	global_load_dword v203, v[14:15], off nt
.LBB0_2185:
	s_or_b64 exec, exec, s[20:21]
	s_and_saveexec_b64 s[20:21], vcc
	s_cbranch_execz .LBB0_2187
	v_add3_u32 v14, v1, s6, 8
	v_ashrrev_i32_e32 v15, 31, v14
	v_lshlrev_b64 v[14:15], 11, v[14:15]
	v_lshl_add_u64 v[14:15], v[6:7], 0, v[14:15]
	global_load_dword v204, v[14:15], off nt
.LBB0_2187:
	s_or_b64 exec, exec, s[20:21]
	s_and_saveexec_b64 s[20:21], vcc
	s_cbranch_execz .LBB0_2189
	v_add3_u32 v14, v1, s6, 10
	v_ashrrev_i32_e32 v15, 31, v14
	v_lshlrev_b64 v[14:15], 11, v[14:15]
	v_lshl_add_u64 v[14:15], v[6:7], 0, v[14:15]
	global_load_dword v205, v[14:15], off nt
.LBB0_2189:
	s_or_b64 exec, exec, s[20:21]
	s_and_saveexec_b64 s[20:21], vcc
	s_cbranch_execz .LBB0_2191
	v_add3_u32 v14, v1, s6, 12
	v_ashrrev_i32_e32 v15, 31, v14
	v_lshlrev_b64 v[14:15], 11, v[14:15]
	v_lshl_add_u64 v[14:15], v[6:7], 0, v[14:15]
	global_load_dword v206, v[14:15], off nt
.LBB0_2191:
	s_or_b64 exec, exec, s[20:21]
	s_and_saveexec_b64 s[20:21], vcc
	s_cbranch_execz .LBB0_2176
	v_add3_u32 v14, v1, s6, 14
	v_ashrrev_i32_e32 v15, 31, v14
	v_lshlrev_b64 v[14:15], 11, v[14:15]
	v_lshl_add_u64 v[14:15], v[6:7], 0, v[14:15]
	global_load_dword v207, v[14:15], off nt
	s_branch .LBB0_2176

.LBB0_2196:
	s_or_b64 exec, exec, s[20:21]
	s_add_i32 s6, s6, 16
	s_waitcnt vmcnt(0)
	ds_write_b32 v6, v207 offset:1848
	ds_write_b32 v6, v200
	ds_write_b32 v6, v201 offset:264
	ds_write_b32 v6, v202 offset:528
	ds_write_b32 v6, v203 offset:792
	ds_write_b32 v6, v204 offset:1056
	ds_write_b32 v6, v205 offset:1320
	ds_write_b32 v6, v206 offset:1584
	s_cmp_eq_u32 s6, 64
	v_add_u32_e32 v6, 0x840, v6
	s_cbranch_scc1 .LBB0_2194
.LBB0_2197:
	v_mov_b32_e32 v200, 0
	v_mov_b32_e32 v201, 0
	v_mov_b32_e32 v202, 0
	v_mov_b32_e32 v203, 0
	v_mov_b32_e32 v204, 0
	v_mov_b32_e32 v205, 0
	v_mov_b32_e32 v206, 0
	v_mov_b32_e32 v207, 0
	s_and_saveexec_b64 s[20:21], vcc
	s_cbranch_execz .LBB0_2199
	v_add_u32_e32 v14, s6, v0
	v_ashrrev_i32_e32 v15, 31, v14
	v_lshlrev_b64 v[14:15], 11, v[14:15]
	v_lshl_add_u64 v[14:15], v[4:5], 0, v[14:15]
	global_load_dword v200, v[14:15], off nt
.LBB0_2199:
	s_or_b64 exec, exec, s[20:21]
	s_and_saveexec_b64 s[20:21], vcc
	s_cbranch_execz .LBB0_2201
	v_add3_u32 v14, v0, s6, 2
	v_ashrrev_i32_e32 v15, 31, v14
	v_lshlrev_b64 v[14:15], 11, v[14:15]
	v_lshl_add_u64 v[14:15], v[4:5], 0, v[14:15]
	global_load_dword v201, v[14:15], off nt
.LBB0_2201:
	s_or_b64 exec, exec, s[20:21]
	s_and_saveexec_b64 s[20:21], vcc
	s_cbranch_execz .LBB0_2203
	v_add3_u32 v14, v0, s6, 4
	v_ashrrev_i32_e32 v15, 31, v14
	v_lshlrev_b64 v[14:15], 11, v[14:15]
	v_lshl_add_u64 v[14:15], v[4:5], 0, v[14:15]
	global_load_dword v202, v[14:15], off nt
.LBB0_2203:
	s_or_b64 exec, exec, s[20:21]
	s_and_saveexec_b64 s[20:21], vcc
	s_cbranch_execz .LBB0_2205
	v_add3_u32 v14, v0, s6, 6
	v_ashrrev_i32_e32 v15, 31, v14
	v_lshlrev_b64 v[14:15], 11, v[14:15]
	v_lshl_add_u64 v[14:15], v[4:5], 0, v[14:15]
	global_load_dword v203, v[14:15], off nt
.LBB0_2205:
	s_or_b64 exec, exec, s[20:21]
	s_and_saveexec_b64 s[20:21], vcc
	s_cbranch_execz .LBB0_2207
	v_add3_u32 v14, v0, s6, 8
	v_ashrrev_i32_e32 v15, 31, v14
	v_lshlrev_b64 v[14:15], 11, v[14:15]
	v_lshl_add_u64 v[14:15], v[4:5], 0, v[14:15]
	global_load_dword v204, v[14:15], off nt
.LBB0_2207:
	s_or_b64 exec, exec, s[20:21]
	s_and_saveexec_b64 s[20:21], vcc
	s_cbranch_execz .LBB0_2209
	v_add3_u32 v14, v0, s6, 10
	v_ashrrev_i32_e32 v15, 31, v14
	v_lshlrev_b64 v[14:15], 11, v[14:15]
	v_lshl_add_u64 v[14:15], v[4:5], 0, v[14:15]
	global_load_dword v205, v[14:15], off nt
.LBB0_2209:
	s_or_b64 exec, exec, s[20:21]
	s_and_saveexec_b64 s[20:21], vcc
	s_cbranch_execz .LBB0_2211
	v_add3_u32 v14, v0, s6, 12
	v_ashrrev_i32_e32 v15, 31, v14
	v_lshlrev_b64 v[14:15], 11, v[14:15]
	v_lshl_add_u64 v[14:15], v[4:5], 0, v[14:15]
	global_load_dword v206, v[14:15], off nt
.LBB0_2211:
	s_or_b64 exec, exec, s[20:21]
	s_and_saveexec_b64 s[20:21], vcc
	s_cbranch_execz .LBB0_2196
	v_add3_u32 v14, v0, s6, 14
	v_ashrrev_i32_e32 v15, 31, v14
	v_lshlrev_b64 v[14:15], 11, v[14:15]
	v_lshl_add_u64 v[14:15], v[4:5], 0, v[14:15]
	global_load_dword v207, v[14:15], off nt
	s_branch .LBB0_2196

.LBB0_2218:
	v_mov_b32_e32 v200, 0
	v_mov_b32_e32 v201, 0
	v_mov_b32_e32 v202, 0
	v_mov_b32_e32 v203, 0
	v_mov_b32_e32 v204, 0
	v_mov_b32_e32 v205, 0
	v_mov_b32_e32 v206, 0
	v_mov_b32_e32 v207, 0
	s_and_saveexec_b64 s[20:21], vcc
	s_cbranch_execz .LBB0_2220
	v_add_u32_e32 v10, s6, v0
	v_ashrrev_i32_e32 v11, 31, v10
	v_lshlrev_b64 v[10:11], 11, v[10:11]
	v_lshl_add_u64 v[10:11], v[4:5], 0, v[10:11]
	global_load_dword v200, v[10:11], off nt
.LBB0_2220:
	s_or_b64 exec, exec, s[20:21]
	s_and_saveexec_b64 s[20:21], vcc
	s_cbranch_execz .LBB0_2222
	v_add3_u32 v10, v0, s6, 2
	v_ashrrev_i32_e32 v11, 31, v10
	v_lshlrev_b64 v[10:11], 11, v[10:11]
	v_lshl_add_u64 v[10:11], v[4:5], 0, v[10:11]
	global_load_dword v201, v[10:11], off nt
.LBB0_2222:
	s_or_b64 exec, exec, s[20:21]
	s_and_saveexec_b64 s[20:21], vcc
	s_cbranch_execz .LBB0_2224
	v_add3_u32 v10, v0, s6, 4
	v_ashrrev_i32_e32 v11, 31, v10
	v_lshlrev_b64 v[10:11], 11, v[10:11]
	v_lshl_add_u64 v[10:11], v[4:5], 0, v[10:11]
	global_load_dword v202, v[10:11], off nt
.LBB0_2224:
	s_or_b64 exec, exec, s[20:21]
	s_and_saveexec_b64 s[20:21], vcc
	s_cbranch_execz .LBB0_2226
	v_add3_u32 v10, v0, s6, 6
	v_ashrrev_i32_e32 v11, 31, v10
	v_lshlrev_b64 v[10:11], 11, v[10:11]
	v_lshl_add_u64 v[10:11], v[4:5], 0, v[10:11]
	global_load_dword v203, v[10:11], off nt
.LBB0_2226:
	s_or_b64 exec, exec, s[20:21]
	s_and_saveexec_b64 s[20:21], vcc
	s_cbranch_execz .LBB0_2228
	v_add3_u32 v10, v0, s6, 8
	v_ashrrev_i32_e32 v11, 31, v10
	v_lshlrev_b64 v[10:11], 11, v[10:11]
	v_lshl_add_u64 v[10:11], v[4:5], 0, v[10:11]
	global_load_dword v204, v[10:11], off nt
.LBB0_2228:
	s_or_b64 exec, exec, s[20:21]
	s_and_saveexec_b64 s[20:21], vcc
	s_cbranch_execz .LBB0_2230
	v_add3_u32 v10, v0, s6, 10
	v_ashrrev_i32_e32 v11, 31, v10
	v_lshlrev_b64 v[10:11], 11, v[10:11]
	v_lshl_add_u64 v[10:11], v[4:5], 0, v[10:11]
	global_load_dword v205, v[10:11], off nt
.LBB0_2230:
	s_or_b64 exec, exec, s[20:21]
	s_and_saveexec_b64 s[20:21], vcc
	s_cbranch_execz .LBB0_2232
	v_add3_u32 v10, v0, s6, 12
	v_ashrrev_i32_e32 v11, 31, v10
	v_lshlrev_b64 v[10:11], 11, v[10:11]
	v_lshl_add_u64 v[10:11], v[4:5], 0, v[10:11]
	global_load_dword v206, v[10:11], off nt
.LBB0_2232:
	s_or_b64 exec, exec, s[20:21]
	s_and_saveexec_b64 s[20:21], vcc
	s_cbranch_execz .LBB0_2217
	v_add3_u32 v10, v0, s6, 14
	v_ashrrev_i32_e32 v11, 31, v10
	v_lshlrev_b64 v[10:11], 11, v[10:11]
	v_lshl_add_u64 v[10:11], v[4:5], 0, v[10:11]
	global_load_dword v207, v[10:11], off nt
	s_branch .LBB0_2217

.LBB0_2238:
	s_add_u32 s22, s22, 0x58000
	s_addc_u32 s23, s23, 0
	s_waitcnt vmcnt(0)
	ds_write_b32 v0, v207 offset:1848
	ds_write_b32 v0, v200
	ds_write_b32 v0, v201 offset:264
	ds_write_b32 v0, v202 offset:528
	ds_write_b32 v0, v203 offset:792
	ds_write_b32 v0, v204 offset:1056
	ds_write_b32 v0, v205 offset:1320
	ds_write_b32 v0, v206 offset:1584
	s_cmp_eq_u32 s22, 0x160000
	v_add_u32_e32 v0, 0x840, v0
	s_cbranch_scc1 .LBB0_2236
.LBB0_2239:
	v_mov_b32_e32 v200, 0
	v_mov_b32_e32 v201, 0
	v_mov_b32_e32 v202, 0
	v_mov_b32_e32 v203, 0
	v_mov_b32_e32 v204, 0
	v_mov_b32_e32 v205, 0
	v_mov_b32_e32 v206, 0
	v_mov_b32_e32 v207, 0
	s_and_b64 vcc, exec, s[10:11]
	s_cbranch_vccnz .LBB0_2241
	v_lshl_add_u64 v[34:35], v[18:19], 0, s[22:23]
	global_load_dword v200, v[34:35], off nt
.LBB0_2241:
	s_and_b64 vcc, exec, s[10:11]
	s_cbranch_vccnz .LBB0_2243
	v_lshl_add_u64 v[34:35], v[16:17], 0, s[22:23]
	global_load_dword v201, v[34:35], off nt
.LBB0_2243:
	s_and_b64 vcc, exec, s[10:11]
	s_cbranch_vccnz .LBB0_2245
	v_lshl_add_u64 v[34:35], v[14:15], 0, s[22:23]
	global_load_dword v202, v[34:35], off nt
.LBB0_2245:
	s_and_b64 vcc, exec, s[10:11]
	s_cbranch_vccnz .LBB0_2247
	v_lshl_add_u64 v[34:35], v[12:13], 0, s[22:23]
	global_load_dword v203, v[34:35], off nt
.LBB0_2247:
	s_and_b64 vcc, exec, s[10:11]
	s_cbranch_vccnz .LBB0_2249
	v_lshl_add_u64 v[34:35], v[10:11], 0, s[22:23]
	global_load_dword v204, v[34:35], off nt
.LBB0_2249:
	s_and_b64 vcc, exec, s[10:11]
	s_cbranch_vccnz .LBB0_2251
	v_lshl_add_u64 v[34:35], v[8:9], 0, s[22:23]
	global_load_dword v205, v[34:35], off nt
.LBB0_2251:
	s_and_b64 vcc, exec, s[10:11]
	s_cbranch_vccnz .LBB0_2253
	v_lshl_add_u64 v[34:35], v[6:7], 0, s[22:23]
	global_load_dword v206, v[34:35], off nt
.LBB0_2253:
	s_and_b64 vcc, exec, s[10:11]
	s_cbranch_vccnz .LBB0_2238
	v_lshl_add_u64 v[34:35], v[4:5], 0, s[22:23]
	global_load_dword v207, v[34:35], off nt
	s_branch .LBB0_2238

.LBB0_2259:
	s_or_b64 exec, exec, s[16:17]
	s_add_i32 s4, s4, 16
	s_waitcnt vmcnt(0)
	ds_write_b32 v8, v207 offset:1848
	ds_write_b32 v8, v200
	ds_write_b32 v8, v201 offset:264
	ds_write_b32 v8, v202 offset:528
	ds_write_b32 v8, v203 offset:792
	ds_write_b32 v8, v204 offset:1056
	ds_write_b32 v8, v205 offset:1320
	ds_write_b32 v8, v206 offset:1584
	s_cmp_eq_u32 s4, 64
	v_add_u32_e32 v8, 0x840, v8
	s_cbranch_scc1 .LBB0_2257
.LBB0_2260:
	v_mov_b32_e32 v200, 0
	v_mov_b32_e32 v201, 0
	v_mov_b32_e32 v202, 0
	v_mov_b32_e32 v203, 0
	v_mov_b32_e32 v204, 0
	v_mov_b32_e32 v205, 0
	v_mov_b32_e32 v206, 0
	v_mov_b32_e32 v207, 0
	s_and_saveexec_b64 s[16:17], vcc
	s_cbranch_execz .LBB0_2262
	v_add_u32_e32 v10, s4, v0
	v_ashrrev_i32_e32 v11, 31, v10
	v_lshlrev_b64 v[10:11], 12, v[10:11]
	v_lshl_add_u64 v[10:11], v[4:5], 0, v[10:11]
	global_load_dword v200, v[10:11], off nt
.LBB0_2262:
	s_or_b64 exec, exec, s[16:17]
	s_and_saveexec_b64 s[16:17], vcc
	s_cbranch_execz .LBB0_2264
	v_add3_u32 v10, v0, s4, 2
	v_ashrrev_i32_e32 v11, 31, v10
	v_lshlrev_b64 v[10:11], 12, v[10:11]
	v_lshl_add_u64 v[10:11], v[4:5], 0, v[10:11]
	global_load_dword v201, v[10:11], off nt
.LBB0_2264:
	s_or_b64 exec, exec, s[16:17]
	s_and_saveexec_b64 s[16:17], vcc
	s_cbranch_execz .LBB0_2266
	v_add3_u32 v10, v0, s4, 4
	v_ashrrev_i32_e32 v11, 31, v10
	v_lshlrev_b64 v[10:11], 12, v[10:11]
	v_lshl_add_u64 v[10:11], v[4:5], 0, v[10:11]
	global_load_dword v202, v[10:11], off nt
.LBB0_2266:
	s_or_b64 exec, exec, s[16:17]
	s_and_saveexec_b64 s[16:17], vcc
	s_cbranch_execz .LBB0_2268
	v_add3_u32 v10, v0, s4, 6
	v_ashrrev_i32_e32 v11, 31, v10
	v_lshlrev_b64 v[10:11], 12, v[10:11]
	v_lshl_add_u64 v[10:11], v[4:5], 0, v[10:11]
	global_load_dword v203, v[10:11], off nt
.LBB0_2268:
	s_or_b64 exec, exec, s[16:17]
	s_and_saveexec_b64 s[16:17], vcc
	s_cbranch_execz .LBB0_2270
	v_add3_u32 v10, v0, s4, 8
	v_ashrrev_i32_e32 v11, 31, v10
	v_lshlrev_b64 v[10:11], 12, v[10:11]
	v_lshl_add_u64 v[10:11], v[4:5], 0, v[10:11]
	global_load_dword v204, v[10:11], off nt
.LBB0_2270:
	s_or_b64 exec, exec, s[16:17]
	s_and_saveexec_b64 s[16:17], vcc
	s_cbranch_execz .LBB0_2272
	v_add3_u32 v10, v0, s4, 10
	v_ashrrev_i32_e32 v11, 31, v10
	v_lshlrev_b64 v[10:11], 12, v[10:11]
	v_lshl_add_u64 v[10:11], v[4:5], 0, v[10:11]
	global_load_dword v205, v[10:11], off nt
.LBB0_2272:
	s_or_b64 exec, exec, s[16:17]
	s_and_saveexec_b64 s[16:17], vcc
	s_cbranch_execz .LBB0_2274
	v_add3_u32 v10, v0, s4, 12
	v_ashrrev_i32_e32 v11, 31, v10
	v_lshlrev_b64 v[10:11], 12, v[10:11]
	v_lshl_add_u64 v[10:11], v[4:5], 0, v[10:11]
	global_load_dword v206, v[10:11], off nt
.LBB0_2274:
	s_or_b64 exec, exec, s[16:17]
	s_and_saveexec_b64 s[16:17], vcc
	s_cbranch_execz .LBB0_2259
	v_add3_u32 v10, v0, s4, 14
	v_ashrrev_i32_e32 v11, 31, v10
	v_lshlrev_b64 v[10:11], 12, v[10:11]
	v_lshl_add_u64 v[10:11], v[4:5], 0, v[10:11]
	global_load_dword v207, v[10:11], off nt
	s_branch .LBB0_2259

.LBB0_3143:
	s_or_b64 exec, exec, s[10:11]
	s_mov_b32 s0, s64
	s_waitcnt lgkmcnt(0)
	s_barrier
	s_lshl_b32 s0, s0, 6
	v_readlane_b32 s1, v248, 3
	s_add_i32 s0, s0, s1
	v_mbcnt_lo_u32_b32 v1, -1, 0
	v_mbcnt_hi_u32_b32 v1, -1, v1
	s_mov_b64 s[14:15], s[62:63]
	v_add_u32_e32 v0, s0, v1
	v_ashrrev_i32_e32 v34, 4, v0
	s_mov_b32 s0, 0x80000
	v_cmp_gt_i32_e32 vcc, s0, v34
	s_and_saveexec_b64 s[10:11], vcc
	s_cbranch_execz .LBB0_3148
	s_load_dwordx2 s[12:13], s[14:15], 0xd8
	s_load_dwordx2 s[8:9], s[14:15], 0x40
	s_load_dwordx4 s[4:7], s[14:15], 0x88
	v_lshlrev_b32_e32 v1, 2, v1
	v_and_b32_e32 v1, 60, v1
	v_bfe_u32 v4, v0, 4, 3
	v_lshl_or_b32 v0, v4, 6, v1
	v_mov_b32_e32 v13, 0
	v_lshlrev_b32_e32 v12, 2, v0
	s_waitcnt lgkmcnt(0)
	v_lshl_add_u64 v[14:15], s[4:5], 0, v[12:13]
	v_lshl_add_u64 v[16:17], s[6:7], 0, v[12:13]
	v_lshl_add_u64 v[2:3], s[8:9], 0, v[12:13]
	s_mov_b64 s[4:5], 0x2c00
	v_lshlrev_b32_e32 v12, 2, v4
	v_readlane_b32 s0, v248, 0
	v_lshl_add_u64 v[18:19], v[2:3], 0, s[4:5]
	v_lshl_add_u64 v[2:3], s[12:13], 0, v[12:13]
	s_mov_b64 s[4:5], 0x2200000
	v_lshlrev_b32_e32 v12, 1, v0
	v_readlane_b32 s1, v248, 1
	v_lshl_add_u64 v[20:21], v[2:3], 0, s[4:5]
	v_lshl_add_u64 v[2:3], s[12:13], 0, v[12:13]
	s_mov_b64 s[4:5], 0x16c00000
	s_lshl_b32 s0, s0, 5
	v_lshl_add_u64 v[22:23], v[2:3], 0, s[4:5]
	s_mov_b64 s[14:15], 0
	v_lshlrev_b32_e32 v12, 1, v0
	s_mov_b64 s[16:17], 0xac00400
	s_movk_i32 s1, 0x1220
	s_mov_b64 s[18:19], 0x22c01400
	v_mov_b32_e32 v35, 0x3a27c5ac
	s_mov_b32 s3, 0x7ffff
	global_load_dwordx4 v[50:53], v[14:15], off offset:2048
	global_load_dwordx4 v[54:57], v[16:17], off offset:2048
	global_load_dwordx4 v[58:61], v[18:19], off
	v_mov_b32_e32 v86, 0xffffe5e0
	v_mov_b32_e32 v87, 0xffff
	v_ashrrev_i32_e32 v76, 3, v34
	v_min_i32_e32 v76, v76, v87
	v_ashrrev_i32_e32 v77, 31, v76
	v_lshlrev_b64 v[78:79], 11, v[76:77]
	v_lshl_add_u64 v[80:81], s[12:13], 0, v[78:79]
	v_lshl_add_u64 v[74:75], v[80:81], 0, v[12:13]
	v_lshl_add_u64 v[74:75], v[74:75], 0, s[16:17]
	v_mad_i64_i32 v[80:81], vcc, v76, s1, v[80:81]
	v_lshl_add_u64 v[80:81], v[80:81], 0, v[12:13]
	v_lshl_add_u64 v[80:81], v[80:81], 0, s[18:19]
	global_load_dwordx2 v[64:65], v[74:75], off
	global_load_dwordx2 v[66:67], v[80:81], off
	v_and_b32_e32 v82, 0xfff8, v34
	v_cmp_ne_u32_e32 vcc, 0, v82
	v_lshlrev_b64 v[78:79], 10, v[76:77]
	v_lshl_add_u64 v[78:79], v[22:23], 0, v[78:79]
	v_cndmask_b32_e64 v73, 0, 1, vcc
	v_cndmask_b32_e32 v82, 0, v86, vcc
	v_ashrrev_i32_e32 v83, 31, v82
	v_lshl_add_u64 v[84:85], v[80:81], 0, v[82:83]
	global_load_dwordx2 v[68:69], v[84:85], off
	global_load_dwordx2 v[70:71], v[78:79], off
	v_lshlrev_b64 v[78:79], 5, v[76:77]
	v_lshl_add_u64 v[78:79], v[20:21], 0, v[78:79]
	global_load_dword v72, v[78:79], off
	s_waitcnt vmcnt(0)
.Lpost_loop_P1:
	v_mov_b64_e32 v[30:31], v[64:65]
	v_mov_b64_e32 v[28:29], v[66:67]
	v_mov_b64_e32 v[62:63], v[68:69]
	v_mov_b64_e32 v[32:33], v[70:71]
	v_mov_b32_e32 v24, v72
	v_mov_b64_e32 v[26:27], v[74:75]
	v_mov_b32_e32 v89, v73
	v_add_u32_e32 v88, s0, v34
	v_ashrrev_i32_e32 v76, 3, v88
	v_min_i32_e32 v76, v76, v87
	v_ashrrev_i32_e32 v77, 31, v76
	v_lshlrev_b64 v[78:79], 11, v[76:77]
	v_lshl_add_u64 v[80:81], s[12:13], 0, v[78:79]
	v_lshl_add_u64 v[74:75], v[80:81], 0, v[12:13]
	v_lshl_add_u64 v[74:75], v[74:75], 0, s[16:17]
	v_mad_i64_i32 v[80:81], vcc, v76, s1, v[80:81]
	v_lshl_add_u64 v[80:81], v[80:81], 0, v[12:13]
	v_lshl_add_u64 v[80:81], v[80:81], 0, s[18:19]
	global_load_dwordx2 v[64:65], v[74:75], off
	global_load_dwordx2 v[66:67], v[80:81], off
	v_and_b32_e32 v82, 0xfff8, v88
	v_cmp_ne_u32_e32 vcc, 0, v82
	v_lshlrev_b64 v[78:79], 10, v[76:77]
	v_lshl_add_u64 v[78:79], v[22:23], 0, v[78:79]
	v_cndmask_b32_e64 v73, 0, 1, vcc
	v_cndmask_b32_e32 v82, 0, v86, vcc
	v_ashrrev_i32_e32 v83, 31, v82
	v_lshl_add_u64 v[84:85], v[80:81], 0, v[82:83]
	global_load_dwordx2 v[68:69], v[84:85], off
	global_load_dwordx2 v[70:71], v[78:79], off
	v_lshlrev_b64 v[78:79], 5, v[76:77]
	v_lshl_add_u64 v[78:79], v[20:21], 0, v[78:79]
	global_load_dword v72, v[78:79], off
	v_lshlrev_b32_e32 v36, 16, v62
	v_and_b32_e32 v38, 0xffff0000, v62
	v_lshlrev_b32_e32 v37, 16, v63
	v_and_b32_e32 v39, 0xffff0000, v63
	v_cmp_ne_u32_e32 vcc, 0, v89
	v_lshlrev_b32_e32 v41, 16, v31
	v_lshlrev_b32_e32 v40, 16, v30
	v_cndmask_b32_e32 v36, 0, v36, vcc
	v_cndmask_b32_e32 v37, 0, v37, vcc
	v_cndmask_b32_e32 v38, 0, v38, vcc
	v_cndmask_b32_e32 v39, 0, v39, vcc
	v_and_b32_e32 v31, 0xffff0000, v31
	v_and_b32_e32 v30, 0xffff0000, v30
	v_lshlrev_b32_e32 v42, 16, v28
	v_and_b32_e32 v43, 0xffff0000, v28
	v_lshlrev_b32_e32 v28, 16, v29
	v_sub_f32_e32 v45, v38, v43
	v_sub_f32_e32 v44, v36, v42
	v_sub_f32_e32 v38, v37, v28
	v_pk_add_f32 v[36:37], v[40:41], v[30:31]
	v_and_b32_e32 v29, 0xffff0000, v29
	v_add_f32_e32 v25, v36, v37
	v_sub_f32_e32 v39, v39, v29
	v_pk_fma_f32 v[10:11], v[60:61], v[38:39], v[28:29]
	v_add_f32_dpp v25, v25, v25 quad_perm:[1,0,3,2] row_mask:0xf bank_mask:0xf bound_ctrl:1
	v_pk_fma_f32 v[8:9], v[58:59], v[44:45], v[42:43]
	s_nop 0
	v_add_f32_dpp v25, v25, v25 quad_perm:[2,3,0,1] row_mask:0xf bank_mask:0xf bound_ctrl:1
	s_nop 1
	v_add_f32_dpp v25, v25, v25 row_half_mirror row_mask:0xf bank_mask:0xf bound_ctrl:1
	s_nop 1
	v_add_f32_dpp v25, v25, v25 row_ror:8 row_mask:0xf bank_mask:0xf bound_ctrl:1
	v_fmac_f32_e32 v30, 0xbc800000, v25
	v_fmac_f32_e32 v31, 0xbc800000, v25
	v_fmac_f32_e32 v41, 0xbc800000, v25
	v_fmac_f32_e32 v40, 0xbc800000, v25
	v_mov_b32_e32 v36, v41
	v_mov_b32_e32 v37, v31
	v_mov_b32_e32 v41, v30
	v_pk_mul_f32 v[30:31], v[36:37], v[36:37]
	v_pk_mul_f32 v[46:47], v[40:41], v[40:41]
	s_nop 0
	v_pk_mov_b32 v[48:49], v[46:47], v[30:31] op_sel:[1,0]
	v_mov_b32_e32 v47, v31
	v_pk_add_f32 v[30:31], v[48:49], v[46:47]
	s_nop 0
	v_add_f32_e32 v25, v30, v31
	s_nop 1
	v_add_f32_dpp v25, v25, v25 quad_perm:[1,0,3,2] row_mask:0xf bank_mask:0xf bound_ctrl:1
	s_nop 1
	v_add_f32_dpp v25, v25, v25 quad_perm:[2,3,0,1] row_mask:0xf bank_mask:0xf bound_ctrl:1
	s_nop 1
	v_add_f32_dpp v25, v25, v25 row_half_mirror row_mask:0xf bank_mask:0xf bound_ctrl:1
	s_nop 1
	v_add_f32_dpp v25, v25, v25 row_ror:8 row_mask:0xf bank_mask:0xf bound_ctrl:1
	v_fmamk_f32 v25, v25, 0x3c800000, v35
	v_rsq_f32_e32 v30, v25
	s_nop 0
	v_pk_mul_f32 v[28:29], v[40:41], v[30:31] op_sel_hi:[1,0]
	v_pk_mul_f32 v[30:31], v[36:37], v[30:31] op_sel_hi:[1,0]
	v_pk_fma_f32 v[0:1], v[50:51], v[28:29], v[54:55]
	v_pk_fma_f32 v[2:3], v[52:53], v[30:31], v[56:57]
	v_lshlrev_b32_e32 v4, 16, v32
	v_and_b32_e32 v5, 0xffff0000, v32
	v_lshlrev_b32_e32 v6, 16, v33
	v_and_b32_e32 v7, 0xffff0000, v33
	v_pk_fma_f32 v[0:1], v[8:9], v[24:25], v[0:1] op_sel_hi:[1,0,1]
	v_pk_fma_f32 v[2:3], v[10:11], v[24:25], v[2:3] op_sel_hi:[1,0,1]
	v_pk_mul_f32 v[0:1], v[0:1], v[4:5]
	v_pk_mul_f32 v[2:3], v[2:3], v[6:7]
	v_cvt_pk_bf16_f32 v0, v0, v1
	v_cvt_pk_bf16_f32 v1, v2, v3
	global_store_dwordx2 v[26:27], v[0:1], off
	v_mov_b32_e32 v34, v88
	v_cmp_lt_i32_e32 vcc, s3, v34
	s_or_b64 s[14:15], vcc, s[14:15]
	s_waitcnt vmcnt(1)
	s_andn2_b64 exec, exec, s[14:15]
	s_cbranch_execnz .Lpost_loop_P1
	s_branch .LBB0_3148

.LBB0_3542:
	s_or_b64 exec, exec, s[20:21]
	s_add_i32 s7, s7, 16
	s_waitcnt vmcnt(0)
	ds_write_b32 v8, v207 offset:1848
	ds_write_b32 v8, v200
	ds_write_b32 v8, v201 offset:264
	ds_write_b32 v8, v202 offset:528
	ds_write_b32 v8, v203 offset:792
	ds_write_b32 v8, v204 offset:1056
	ds_write_b32 v8, v205 offset:1320
	ds_write_b32 v8, v206 offset:1584
	s_cmp_eq_u32 s7, 64
	v_add_u32_e32 v8, 0x840, v8
	s_cbranch_scc1 .LBB0_3538
.LBB0_3543:
	v_mov_b32_e32 v200, 0
	v_mov_b32_e32 v201, 0
	v_mov_b32_e32 v202, 0
	v_mov_b32_e32 v203, 0
	v_mov_b32_e32 v204, 0
	v_mov_b32_e32 v205, 0
	v_mov_b32_e32 v206, 0
	v_mov_b32_e32 v207, 0
	s_and_saveexec_b64 s[20:21], vcc
	s_cbranch_execz .LBB0_3545
	v_add_u32_e32 v10, s7, v0
	v_mad_i64_i32 v[10:11], s[8:9], v10, s4, v[4:5]
	global_load_dword v200, v[10:11], off nt
.LBB0_3545:
	s_or_b64 exec, exec, s[20:21]
	s_and_saveexec_b64 s[20:21], vcc
	s_cbranch_execz .LBB0_3547
	v_add3_u32 v9, v0, s7, 2
	v_mad_i64_i32 v[10:11], s[8:9], v9, s4, v[4:5]
	global_load_dword v201, v[10:11], off nt
.LBB0_3547:
	s_or_b64 exec, exec, s[20:21]
	s_and_saveexec_b64 s[20:21], vcc
	s_cbranch_execz .LBB0_3549
	v_add3_u32 v10, v0, s7, 4
	v_mad_i64_i32 v[10:11], s[8:9], v10, s4, v[4:5]
	global_load_dword v202, v[10:11], off nt
.LBB0_3549:
	s_or_b64 exec, exec, s[20:21]
	s_and_saveexec_b64 s[20:21], vcc
	s_cbranch_execz .LBB0_3551
	v_add3_u32 v9, v0, s7, 6
	v_mad_i64_i32 v[10:11], s[8:9], v9, s4, v[4:5]
	global_load_dword v203, v[10:11], off nt
.LBB0_3551:
	s_or_b64 exec, exec, s[20:21]
	s_and_saveexec_b64 s[20:21], vcc
	s_cbranch_execz .LBB0_3553
	v_add3_u32 v10, v0, s7, 8
	v_mad_i64_i32 v[10:11], s[8:9], v10, s4, v[4:5]
	global_load_dword v204, v[10:11], off nt
.LBB0_3553:
	s_or_b64 exec, exec, s[20:21]
	s_and_saveexec_b64 s[20:21], vcc
	s_cbranch_execz .LBB0_3555
	v_add3_u32 v9, v0, s7, 10
	v_mad_i64_i32 v[10:11], s[8:9], v9, s4, v[4:5]
	global_load_dword v205, v[10:11], off nt
.LBB0_3555:
	s_or_b64 exec, exec, s[20:21]
	s_and_saveexec_b64 s[20:21], vcc
	s_cbranch_execz .LBB0_3557
	v_add3_u32 v10, v0, s7, 12
	v_mad_i64_i32 v[10:11], s[8:9], v10, s4, v[4:5]
	global_load_dword v206, v[10:11], off nt
.LBB0_3557:
	s_or_b64 exec, exec, s[20:21]
	s_and_saveexec_b64 s[20:21], vcc
	s_cbranch_execz .LBB0_3542
	v_add3_u32 v9, v0, s7, 14
	v_mad_i64_i32 v[10:11], s[8:9], v9, s4, v[4:5]
	global_load_dword v207, v[10:11], off nt
	s_branch .LBB0_3542
